# v013 + weight-conversion units 244.. moved from the mixer tail to the workgroups idle in the Q-projection GEMM phase
# baseline (speedup 1.0000x reference)
; #define REPBAR(k) do { if (rep + 1 < REPS(k)) xcd_barrier(bar); } while (0)
; #define LAUNDER() do { launder(F); GAS unsigned char* _g = (GAS unsigned char*)ws; asm volatile("" : "+s"(_g)); ws = (unsigned char*)_g; } while (0)
; template <int MODE>
; DI void norm_phase(const Args& a, const Frame& F, int nslab, float sscale, float* RSTD, const float* SSP) {
;     ...
;     if (MODE == 0) {
;         for (int row = F.bid * NTHR + F.tid; row < NP; row += F.G * NTHR) { const f32x4* q = (const f32x4*)(SSP + (size_t)row * 16); const f32x4 p = (q[0] + q[1]) + (q[2] + q[3]);
;             RSTD[row] = 1.f / sqrtf(((p[0] + p[1]) + (p[2] + p[3])) * (1.f / DM) + EPS); }
; __global__ void __launch_bounds__(NTHR, 2) fwd(Args args) {
;     ...
;     for (int l = 0; l < DEPTH; ++l) {
;         const int pb = 1 + l * PH_PER_LAYER;
;     ...
;         if (PH_ON(1) && IN(pb + 0) && l > 0) for (int rep = 0; rep < REPS(1); ++rep) { LAUNDER(); norm_phase<0>(args, F, rep ? 0 : 8, 0.5f, RSITE(4 * l), PSITE(4 * l)); REPBAR(1); }
.LBB0_210:
	s_mov_b32 s100, 0
	s_mul_i32 s0, s90, 15
	s_add_i32 s18, s0, 1
	s_cmp_le_i32 s70, s18
	v_writelane_b32 v249, s0, 24
	s_cselect_b64 s[0:1], -1, 0
	s_cmp_gt_i32 s70, s18
	s_cbranch_scc1 .LBB0_234
	s_cmp_ge_i32 s18, s71
	s_cselect_b64 s[2:3], -1, 0
	s_cmp_eq_u32 s90, 0
	s_cselect_b64 s[4:5], -1, 0
	s_or_b64 s[2:3], s[4:5], s[2:3]
	s_and_b64 vcc, exec, s[2:3]
	s_cbranch_vccnz .LBB0_234
	s_movk_i32 s2, 0x4000
	v_lshl_add_u32 v4, s69, 9, v0
	v_cmp_gt_i32_e32 vcc, s2, v4
	s_and_saveexec_b64 s[4:5], vcc
	v_readlane_b32 s10, v252, 33
	v_readlane_b32 s12, v252, 37
	v_readlane_b32 s8, v252, 35
	v_readlane_b32 s11, v252, 34
	v_readlane_b32 s13, v252, 38
	v_readlane_b32 s9, v252, 36
	s_cbranch_execz .LBB0_215
	v_readlane_b32 s2, v252, 60
	v_readlane_b32 s3, v252, 61
	s_add_u32 s2, s96, s2
	s_waitcnt lgkmcnt(0)
	v_ashrrev_i32_e32 v5, 31, v4
	s_addc_u32 s3, s97, s3
	s_waitcnt vmcnt(0)
	v_lshl_add_u64 v[6:7], v[4:5], 2, s[2:3]
	v_readlane_b32 s2, v252, 62
	v_readlane_b32 s3, v252, 63
	s_add_u32 s2, s96, s2
	v_lshlrev_b64 v[8:9], 6, v[4:5]
	s_addc_u32 s3, s97, s3
	v_lshl_add_u64 v[8:9], s[2:3], 0, v[8:9]
	s_mov_b64 s[6:7], 0

; #define DEAL_LOOP_DYN(F, ctr, N, BODY) do { gu32* _c = (ctr); int u = next_unit(F, _c); while (u < (N)) { const unsigned _t = deal_prefetch(F, _c); BODY; u = deal_publish(F, _t); } __syncthreads(); } while (0)
; #define LAUNDER() do { launder(F); GAS unsigned char* _g = (GAS unsigned char*)ws; asm volatile("" : "+s"(_g)); ws = (unsigned char*)_g; } while (0)
; DI int next_unit(const Frame& F, gu32* ctr) {
;     __syncthreads();
;     if (F.tid == 0) F.MISC[4] = __hip_atomic_fetch_add(ctr, 1u, RLX_AGENT);
;     __syncthreads();
;     return __builtin_amdgcn_readfirstlane((int)F.MISC[4]);
; }
; __global__ void __launch_bounds__(NTHR, 2) fwd(Args args) {
;     ...
;             { LAUNDER(); const int cv0 = BT_EARLY + l * BT_LAYER, cvn = ((l + 1 < DEPTH ? BT_LAYER : BT_LAYER - BT_EARLY)) / CV_PER;
;               DEAL_LOOP_DYN(F, cnt_word(F, l, CNT_CVT), cvn, cvt_unit(args, F, cv0 + u * CV_PER)); }
.Lcvt_entry:
	v_cmp_eq_u32_e64 s[8:9], 0, v0
	s_barrier
	s_and_saveexec_b64 s[0:1], s[8:9]
	v_writelane_b32 v249, s69, 53
	v_writelane_b32 v249, s78, 54
	s_xor_b64 s[0:1], exec, s[0:1]
	s_mov_b32 s33, 0x400000
	v_writelane_b32 v249, s79, 55
	v_writelane_b32 v249, s96, 56
	s_nop 1
	v_writelane_b32 v249, s97, 57
	v_writelane_b32 v249, s8, 45
	s_nop 1
	v_writelane_b32 v249, s9, 46
	s_cbranch_execz .LBB0_1572
	s_mov_b64 s[4:5], exec
	v_mbcnt_lo_u32_b32 v3, s4, 0
	v_mbcnt_hi_u32_b32 v3, s5, v3
	v_cmp_eq_u32_e32 vcc, 0, v3
	s_and_saveexec_b64 s[2:3], vcc
	s_cbranch_execz .LBB0_1571
	s_bcnt1_i32_b64 s4, s[4:5]
	v_mov_b32_e32 v4, s4
	v_readlane_b32 s4, v249, 33
	v_readlane_b32 s5, v249, 34
	s_lshl_b32 s101, s100, 8
	s_add_u32 s4, s4, s101
	s_addc_u32 s5, s5, 0
	s_nop 4
	global_atomic_add v4, v2, v4, s[4:5] offset:2816 sc0

; #define GAS __attribute__((address_space(1)))
; #define LAS __attribute__((address_space(3)))
; DI unsigned pk2(float lo, float hi) { const f32x2 v = {lo, hi}; return __builtin_bit_cast(unsigned, __builtin_convertvector(v, hwbf16x2)); }
; #define DEAL_LOOP_DYN(F, ctr, N, BODY) do { gu32* _c = (ctr); int u = next_unit(F, _c); while (u < (N)) { const unsigned _t = deal_prefetch(F, _c); BODY; u = deal_publish(F, _t); } __syncthreads(); } while (0)
; #define LAUNDER() do { launder(F); GAS unsigned char* _g = (GAS unsigned char*)ws; asm volatile("" : "+s"(_g)); ws = (unsigned char*)_g; } while (0)
; DI void big_load(const BigDesc& d, int tid, f32x4 (&w)[16]) {
; #pragma unroll
;     for (int i = 0; i < 16; ++i) { const int idx = tid + i * NTHR, row = idx >> 7, c4 = idx & 127; w[i] = __builtin_nontemporal_load((const f32x4*)(d.src + (size_t)row * d.N + 4 * c4)); }
; }
; DI void big_to_lds(const BigDesc& d, int tid, const f32x4 (&w)[16], LAS float* T) {
; #pragma unroll
;     for (int i = 0; i < 16; ++i) { const int idx = tid + i * NTHR, row = idx >> 7, c4 = idx & 127; const float g = d.gain ? d.gain[row] : 1.f;
;         LAS float* p = T + row * 513 + 4 * c4; p[0] = w[i][0] * g; p[1] = w[i][1] * g; p[2] = w[i][2] * g; p[3] = w[i][3] * g; }
; }
; DI void big_store(const BigDesc& d, int n0, int tid, const LAS float* T) {
; #pragma unroll
;     for (int j = 0; j < 8; ++j) { const int cidx = tid + j * NTHR, n = cidx >> 3, c = cidx & 7; const LAS float* s = T + (8 * c) * 513 + n;
;         u32x4 o; o.x = pk2(s[0 * 513], s[1 * 513]); o.y = pk2(s[2 * 513], s[3 * 513]); o.z = pk2(s[4 * 513], s[5 * 513]); o.w = pk2(s[6 * 513], s[7 * 513]);
;         const int ng = n0 + n; const int drow = d.map ? 256 * (ng >> 7) + (ng & 127) + (d.map == 2 ? 128 : 0) : ng;
;         *(GAS u32x4*)(d.dst + (size_t)drow * d.ldt + 8 * c) = o; }
; __global__ void __launch_bounds__(NTHR, 2) fwd(Args args) {
;     ...
;             { LAUNDER(); const int cv0 = BT_EARLY + l * BT_LAYER, cvn = ((l + 1 < DEPTH ? BT_LAYER : BT_LAYER - BT_EARLY)) / CV_PER;
;               DEAL_LOOP_DYN(F, cnt_word(F, l, CNT_CVT), cvn, cvt_unit(args, F, cv0 + u * CV_PER)); }
.LBB0_1572:
	s_or_b64 exec, exec, s[0:1]
	v_mov_b32_e32 v3, s79
	s_waitcnt lgkmcnt(0)
	s_barrier
	ds_read_b32 v3, v3
	s_cmp_eq_u32 s90, 3
	s_movk_i32 s0, 0xe0
	s_cselect_b32 s0, s0, 0x1d0
	s_min_i32 s101, s0, 0xf4
	s_sub_i32 s0, s0, 0xf4
	s_cmp_eq_u32 s100, 0
	s_cselect_b32 s0, s101, s0
	v_writelane_b32 v248, s0, 17
	s_waitcnt lgkmcnt(0)
	v_readfirstlane_b32 s6, v3
	s_cmp_ge_i32 s6, s0
	s_cbranch_scc1 .LBB0_1684
	v_lshlrev_b32_e32 v3, 2, v0
	v_and_b32_e32 v4, 0x1fc, v3
	v_add_u32_e32 v3, 0x1000, v0
	v_ashrrev_i32_e32 v84, 7, v3
	v_add_u32_e32 v3, 0x1200, v0
	v_ashrrev_i32_e32 v86, 7, v3
	v_add_u32_e32 v3, 0x1400, v0
	v_ashrrev_i32_e32 v88, 7, v3
	v_add_u32_e32 v3, 0x1600, v0
	v_ashrrev_i32_e32 v90, 7, v3
	v_add_u32_e32 v3, 0x1800, v0
	v_ashrrev_i32_e32 v92, 7, v3
	v_add_u32_e32 v3, 0x1a00, v0
	v_ashrrev_i32_e32 v94, 7, v3
	v_add_u32_e32 v3, 0x1c00, v0
	s_mul_i32 s0, s90, 0x3a0
	v_ashrrev_i32_e32 v96, 7, v3
	v_add_u32_e32 v3, 0x1e00, v0
	s_addk_i32 s0, 0x1e0
	v_add_u32_e32 v5, 0x200, v0
	v_add_u32_e32 v7, 0x400, v0
	v_add_u32_e32 v8, 0x600, v0
	v_add_u32_e32 v9, 0x800, v0
	v_add_u32_e32 v10, 0xa00, v0
	v_add_u32_e32 v11, 0xc00, v0
	v_add_u32_e32 v12, 0xe00, v0
	v_ashrrev_i32_e32 v98, 7, v3
	v_lshlrev_b32_e32 v3, 3, v0
	v_writelane_b32 v248, s0, 0
	v_ashrrev_i32_e32 v68, 7, v0
	v_ashrrev_i32_e32 v70, 7, v5
	v_ashrrev_i32_e32 v72, 7, v7
	v_ashrrev_i32_e32 v74, 7, v8
	v_ashrrev_i32_e32 v76, 7, v9
	v_ashrrev_i32_e32 v78, 7, v10
	v_ashrrev_i32_e32 v80, 7, v11
	v_ashrrev_i32_e32 v82, 7, v12
	s_movk_i32 s0, 0x804
	v_and_b32_e32 v6, 56, v3
	v_lshl_add_u32 v13, v4, 2, 0
	v_mul_lo_u32 v14, v68, s0
	v_mul_lo_u32 v15, v70, s0
	v_mul_lo_u32 v16, v72, s0
	v_mul_lo_u32 v17, v74, s0
	v_mul_lo_u32 v18, v76, s0
	v_mul_lo_u32 v19, v78, s0
	v_mul_lo_u32 v20, v80, s0
	v_mul_lo_u32 v21, v82, s0
	v_mul_lo_u32 v22, v84, s0
	v_mul_lo_u32 v23, v86, s0
	v_mul_lo_u32 v24, v88, s0
	v_mul_lo_u32 v25, v90, s0
	v_mul_lo_u32 v26, v92, s0
	v_mul_lo_u32 v27, v94, s0
	v_mul_lo_u32 v28, v96, s0
	v_mul_lo_u32 v29, v98, s0
	v_mad_u32_u24 v30, v6, s0, 0
	v_ashrrev_i32_e32 v3, 3, v0
	v_ashrrev_i32_e32 v106, 3, v5
	v_ashrrev_i32_e32 v108, 3, v7
	v_ashrrev_i32_e32 v110, 3, v8
	v_ashrrev_i32_e32 v112, 3, v9
	v_ashrrev_i32_e32 v114, 3, v10
	v_ashrrev_i32_e32 v116, 3, v11
	v_ashrrev_i32_e32 v118, 3, v12
	v_ashrrev_i32_e32 v69, 31, v68
	v_ashrrev_i32_e32 v71, 31, v70
	v_ashrrev_i32_e32 v73, 31, v72
	v_ashrrev_i32_e32 v75, 31, v74
	v_ashrrev_i32_e32 v77, 31, v76
	v_ashrrev_i32_e32 v79, 31, v78
	v_ashrrev_i32_e32 v81, 31, v80
	v_ashrrev_i32_e32 v83, 31, v82
	v_ashrrev_i32_e32 v85, 31, v84
	v_ashrrev_i32_e32 v87, 31, v86
	v_ashrrev_i32_e32 v89, 31, v88
	v_ashrrev_i32_e32 v91, 31, v90
	v_ashrrev_i32_e32 v93, 31, v92
	v_ashrrev_i32_e32 v95, 31, v94
	v_ashrrev_i32_e32 v97, 31, v96
	v_ashrrev_i32_e32 v99, 31, v98
	v_lshl_add_u32 v105, v3, 2, v30
	v_lshl_add_u32 v107, v106, 2, v30
	v_lshl_add_u32 v109, v108, 2, v30
	v_lshl_add_u32 v111, v110, 2, v30
	v_lshl_add_u32 v113, v112, 2, v30
	v_lshl_add_u32 v115, v114, 2, v30
	v_lshl_add_u32 v117, v116, 2, v30
	v_lshl_add_u32 v119, v118, 2, v30
	v_lshlrev_b32_e32 v100, 2, v4
	v_add_u32_e32 v120, v13, v15
	v_add_u32_e32 v121, v13, v17
	v_add_u32_e32 v122, v13, v19
	v_add_u32_e32 v123, v13, v21
	v_add_u32_e32 v124, v13, v23
	v_add_u32_e32 v125, v13, v25
	v_add_u32_e32 v126, v13, v27
	v_add_u32_e32 v127, v13, v29
	v_lshlrev_b32_e32 v102, 1, v6
	v_add_u32_e32 v128, v13, v14
	v_add_u32_e32 v129, v13, v16
	v_add_u32_e32 v130, v13, v18
	v_add_u32_e32 v131, v13, v20
	v_add_u32_e32 v132, v13, v22
	v_add_u32_e32 v133, v13, v24
	v_add_u32_e32 v134, v13, v26
	v_add_u32_e32 v135, v13, v28
	s_branch .LBB0_1575

; DI int deal_publish(const Frame& F, unsigned t) {
;     __syncthreads();
;     if (F.tid == 0) F.MISC[4] = t;
;     __syncthreads();
;     return __builtin_amdgcn_readfirstlane((int)F.MISC[4]);
; }
.LBB0_1575:
	v_mov_b32_e32 v136, 0
	s_and_saveexec_b64 s[0:1], s[8:9]
	s_cbranch_execz .LBB0_1579
	s_mov_b64 s[4:5], exec
	v_mbcnt_lo_u32_b32 v4, s4, 0
	v_mbcnt_hi_u32_b32 v4, s5, v4
	v_cmp_eq_u32_e32 vcc, 0, v4
	s_and_saveexec_b64 s[2:3], vcc
	s_cbranch_execz .LBB0_1578
	s_bcnt1_i32_b64 s4, s[4:5]
	v_mov_b32_e32 v5, s4
	v_readlane_b32 s4, v249, 33
	v_readlane_b32 s5, v249, 34
	s_lshl_b32 s101, s100, 8
	s_add_u32 s4, s4, s101
	s_addc_u32 s5, s5, 0
	s_nop 4
	global_atomic_add v5, v2, v5, s[4:5] offset:2816 sc0

; #define LAS __attribute__((address_space(3)))
; DI BigDesc big_desc(const Args& a, int it, int& n0) {
;     const int l = it / BT_LAYER; int r = it % BT_LAYER;
;     unsigned char* ws = a.ws; unsigned char* wl = ws + WS_W + (size_t)l * LW;
;     const size_t oFF = (size_t)l * DM * DFF, oIN = (size_t)l * DM * INW, oDD = (size_t)l * DM * DM, oXQ = (size_t)l * DM * XW;
;     if (r < BT_FF) return big_mk(a.in[I_F1G] + oFF, DM, DFF, a.in[I_F1N] + l * DM, (bf16*)(wl + W_GU1), 0, 1, r, 0, n0); r -= BT_FF;
;     if (r < BT_FF) return big_mk(a.in[I_F1U] + oFF, DM, DFF, a.in[I_F1N] + l * DM, (bf16*)(wl + W_GU1), 0, 2, r, 0, n0); r -= BT_FF;
;     if (r < BT_DN) return big_mk(a.in[I_F1D] + oFF, DFF, DM, nullptr, (bf16*)(wl + W_D1), 0, 0, r, ALD, n0); r -= BT_DN;
;     if (r < BT_IN) return big_mk(a.in[I_WIN] + oIN, DM, INW, a.in[I_MIXN] + l * DM, (bf16*)(wl + W_IN), 0, 0, r, 0, n0); r -= BT_IN;
;     if (r < BT_Q) return big_mk(a.in[I_XWK] + oXQ, DM, XW, a.in[I_MEMNORM] + l * DM, (bf16*)(ws + WS_WKV), l * 1024, 0, r, 0, n0); r -= BT_Q;
;     if (r < BT_Q) return big_mk(a.in[I_XWV] + oXQ, DM, XW, a.in[I_MEMNORM] + l * DM, (bf16*)(ws + WS_WKV), l * 1024 + 512, 0, r, 0, n0); r -= BT_Q;
;     if (r < BT_FF) return big_mk(a.in[I_F2G] + oFF, DM, DFF, a.in[I_F2N] + l * DM, (bf16*)(wl + W_GU2), 0, 1, r, 0, n0); r -= BT_FF;
;     if (r < BT_FF) return big_mk(a.in[I_F2U] + oFF, DM, DFF, a.in[I_F2N] + l * DM, (bf16*)(wl + W_GU2), 0, 2, r, 0, n0); r -= BT_FF;
;     if (r < BT_DN) return big_mk(a.in[I_F2D] + oFF, DFF, DM, nullptr, (bf16*)(wl + W_D2), 0, 0, r, ALD, n0); r -= BT_DN;
;     if (r < BT_OUT) return big_mk(a.in[I_WOUT] + oDD, DM, DM, nullptr, (bf16*)(wl + W_OUT), 0, 0, r, 0, n0); r -= BT_OUT;
;     if (r < BT_Q) return big_mk(a.in[I_XWQ] + oXQ, DM, XW, a.in[I_XN] + l * DM, (bf16*)(wl + W_Q), 0, 0, r, 0, n0); r -= BT_Q;
;     return big_mk(a.in[I_XWO] + oXQ, XW, DM, nullptr, (bf16*)(wl + W_O), 0, 0, r, 0, n0);
; DI void cvt_unit(const Args& a, const Frame& F, int it0) {
;     LAS float* T = (LAS float*)F.lds;
;     int n0 = 0, n1 = 0; f32x4 w[16];
;     BigDesc d = big_desc(a, it0, n0); big_load(d, F.tid, w);
.LBB0_1579:
	s_or_b64 exec, exec, s[0:1]
	s_mul_i32 s101, s100, 0xf4
	s_add_i32 s101, s6, s101
	s_lshl_b32 s0, s101, 1
	v_readlane_b32 s1, v248, 0
	s_add_i32 s18, s1, s0
	s_mul_hi_i32 s0, s18, 0x8d3dcb09
	s_add_i32 s0, s0, s18
	s_lshr_b32 s1, s0, 31
	s_ashr_i32 s0, s0, 9
	s_add_i32 s2, s0, s1
	s_mul_i32 s0, s2, 0x3a0
	s_sub_i32 s21, s18, s0
	s_ashr_i32 s3, s2, 31
	s_mul_i32 s1, s2, 0x3b00000
	v_readlane_b32 s4, v252, 7
	s_mul_hi_i32 s0, s2, 0x3b00000
	s_add_u32 s19, s4, s1
	v_readlane_b32 s1, v252, 8
	s_addc_u32 s20, s1, s0
	s_lshl_b64 s[8:9], s[2:3], 22
	s_cmpk_gt_i32 s21, 0x7f
	s_mov_b64 s[14:15], -1
	s_cbranch_scc0 .LBB0_1620
	s_cmpk_gt_u32 s21, 0xff
	s_cbranch_scc0 .LBB0_1617
	s_cmpk_gt_u32 s21, 0x17f
	s_cbranch_scc0 .LBB0_1614
	s_cmpk_gt_u32 s21, 0x1bf
	s_cbranch_scc0 .LBB0_1611
	s_lshl_b64 s[14:15], s[2:3], 19
	s_cmpk_gt_u32 s21, 0x1cf
	s_mov_b64 s[16:17], -1
	s_cbranch_scc0 .LBB0_1608
	s_cmpk_gt_u32 s21, 0x1df
	s_cbranch_scc0 .LBB0_1605
	s_cmpk_gt_u32 s21, 0x25f
	s_cbranch_scc0 .LBB0_1602
	s_cmpk_gt_u32 s21, 0x2df
	s_mov_b64 s[6:7], -1
	s_cbranch_scc0 .LBB0_1599
	s_cmpk_gt_u32 s21, 0x35f
	s_cbranch_scc0 .LBB0_1596
	s_cmpk_gt_u32 s21, 0x37f
	s_cbranch_scc0 .LBB0_1593
	s_cmpk_gt_u32 s21, 0x38f
	s_mov_b64 s[4:5], -1
	s_cbranch_scc0 .LBB0_1591
	v_readlane_b32 s36, v251, 28
	s_lshl_b64 s[0:1], s[14:15], 2
	v_readlane_b32 s48, v251, 40
	v_readlane_b32 s49, v251, 41
	s_add_u32 s0, s48, s0
	s_addc_u32 s1, s49, s1
	s_lshl_b32 s4, s21, 5
	s_addk_i32 s4, 0xe00
	s_and_b32 s4, s4, 0x1fc0
	s_lshl_b32 s5, s4, 12
	s_add_u32 s10, s0, s5
	s_addc_u32 s11, s1, 0
	s_lshl_b32 s0, s4, 1
	s_add_u32 s0, s19, s0
	s_addc_u32 s1, s20, 0
	s_add_u32 s0, s0, 0x2000000
	v_readlane_b32 s37, v251, 29
	v_readlane_b32 s38, v251, 30
	v_readlane_b32 s39, v251, 31
	v_readlane_b32 s40, v251, 32
	v_readlane_b32 s41, v251, 33
	v_readlane_b32 s42, v251, 34
	v_readlane_b32 s43, v251, 35
	v_readlane_b32 s44, v251, 36
	v_readlane_b32 s45, v251, 37
	v_readlane_b32 s46, v251, 38
	v_readlane_b32 s47, v251, 39
	v_readlane_b32 s50, v251, 42
	v_readlane_b32 s51, v251, 43
	s_addc_u32 s1, s1, 0
	s_mov_b64 s[4:5], 0

; #define DEAL_LOOP_DYN(F, ctr, N, BODY) do { gu32* _c = (ctr); int u = next_unit(F, _c); while (u < (N)) { const unsigned _t = deal_prefetch(F, _c); BODY; u = deal_publish(F, _t); } __syncthreads(); } while (0)
; #define LAUNDER() do { launder(F); GAS unsigned char* _g = (GAS unsigned char*)ws; asm volatile("" : "+s"(_g)); ws = (unsigned char*)_g; } while (0)
; __global__ void __launch_bounds__(NTHR, 2) fwd(Args args) {
;     ...
;             { LAUNDER(); const int cv0 = BT_EARLY + l * BT_LAYER, cvn = ((l + 1 < DEPTH ? BT_LAYER : BT_LAYER - BT_EARLY)) / CV_PER;
;               DEAL_LOOP_DYN(F, cnt_word(F, l, CNT_CVT), cvn, cvt_unit(args, F, cv0 + u * CV_PER)); }
.LBB0_1684:
	v_readlane_b32 s2, v249, 26
	v_readlane_b32 s3, v249, 27
	s_barrier
	s_cmp_eq_u32 s100, 1
	s_cbranch_scc1 .Lg5_ret

; #define DEAL_LOOP_DYN(F, ctr, N, BODY) do { gu32* _c = (ctr); int u = next_unit(F, _c); while (u < (N)) { const unsigned _t = deal_prefetch(F, _c); BODY; u = deal_publish(F, _t); } __syncthreads(); } while (0)
; #define REPBAR(k) do { if (rep + 1 < REPS(k)) xcd_barrier(bar); } while (0)
; #define LAUNDER() do { launder(F); GAS unsigned char* _g = (GAS unsigned char*)ws; asm volatile("" : "+s"(_g)); ws = (unsigned char*)_g; } while (0)
; __global__ void __launch_bounds__(NTHR, 2) fwd(Args args) {
;     ...
;             { LAUNDER(); const int cv0 = BT_EARLY + l * BT_LAYER, cvn = ((l + 1 < DEPTH ? BT_LAYER : BT_LAYER - BT_EARLY)) / CV_PER;
;               DEAL_LOOP_DYN(F, cnt_word(F, l, CNT_CVT), cvn, cvt_unit(args, F, cv0 + u * CV_PER)); }
;     ...
;         if (PH_ON(10) && IN(pb + 9)) for (int rep = 0; rep < REPS(10); ++rep) { LAUNDER(); pg8::Sched S{(const char*)(ws + WS_X), (const char*)(wl + W_Q), DM, DM, MT / 256, XW / 256, DM / 64, F.G, F.bid, nullptr, nullptr, 0, 0, 0, 0, 0};
;             fill_rs_table(F, S, RSITE(4 * l + 2)); EpiQ E{(bf16*)(ws + WS_Q), RS_LDS}; pg8::gemm_phase<EpiQ, true>(F.lds, S, E, F.tid); REPBAR(10); }
.Lg5_cvt:
	v_writelane_b32 v254, s0, 0
	v_writelane_b32 v254, s1, 1
	s_mov_b32 s100, 1
	s_branch .Lcvt_entry
.Lg5_ret:
	s_mov_b32 s100, 0
	v_readlane_b32 s0, v254, 0
	v_readlane_b32 s1, v254, 1
	s_branch .LBB0_1968

; #define LAS __attribute__((address_space(3)))
; __global__ void __launch_bounds__(NTHR, 2) fwd(Args args) {
;     extern __shared__ __attribute__((aligned(16))) unsigned char lds_raw[];
;     Frame F;
;     F.lds = (LAS unsigned char*)lds_raw;
;     F.MISC = (volatile LAS unsigned*)(F.lds + LDSCTL_OFF);
;     F.tid = threadIdx.x; F.lane = F.tid & 63; F.wave = __builtin_amdgcn_readfirstlane(F.tid >> 6);
;     F.G = gridDim.x; F.bid = blockIdx.x;
	.amdhsa_kernel _Z3fwd4Args
		.amdhsa_group_segment_fixed_size 0
		.amdhsa_private_segment_fixed_size 0
		.amdhsa_kernarg_size 696
		.amdhsa_user_sgpr_count 2
		.amdhsa_user_sgpr_dispatch_ptr 0
		.amdhsa_user_sgpr_queue_ptr 0
		.amdhsa_user_sgpr_kernarg_segment_ptr 1
		.amdhsa_user_sgpr_dispatch_id 0
		.amdhsa_user_sgpr_kernarg_preload_length 0
		.amdhsa_user_sgpr_kernarg_preload_offset 0
		.amdhsa_user_sgpr_private_segment_size 0
		.amdhsa_uses_dynamic_stack 0
		.amdhsa_enable_private_segment 0
		.amdhsa_system_sgpr_workgroup_id_x 1
		.amdhsa_system_sgpr_workgroup_id_y 0
		.amdhsa_system_sgpr_workgroup_id_z 0
		.amdhsa_system_sgpr_workgroup_info 0
		.amdhsa_system_vgpr_workitem_id 0
		.amdhsa_next_free_vgpr 256
		.amdhsa_next_free_sgpr 102
		.amdhsa_accum_offset 256
		.amdhsa_reserve_vcc 1
		.amdhsa_float_round_mode_32 0
		.amdhsa_float_round_mode_16_64 0
		.amdhsa_float_denorm_mode_32 3
		.amdhsa_float_denorm_mode_16_64 3
		.amdhsa_dx10_clamp 1
		.amdhsa_ieee_mode 1
		.amdhsa_fp16_overflow 0
		.amdhsa_tg_split 0
		.amdhsa_exception_fp_ieee_invalid_op 0
		.amdhsa_exception_fp_denorm_src 0
		.amdhsa_exception_fp_ieee_div_zero 0
		.amdhsa_exception_fp_ieee_overflow 0
		.amdhsa_exception_fp_ieee_underflow 0
		.amdhsa_exception_fp_ieee_inexact 0
		.amdhsa_exception_int_div_zero 0
	.end_amdhsa_kernel

; __global__ void __launch_bounds__(NTHR, 2) fwd(Args args) {
amdhsa.kernels:
  - .agpr_count:     0
    .args:
      - .offset:         0
        .size:           440
        .value_kind:     by_value
      - .offset:         440
        .size:           4
        .value_kind:     hidden_block_count_x
      - .offset:         444
        .size:           4
        .value_kind:     hidden_block_count_y
      - .offset:         448
        .size:           4
        .value_kind:     hidden_block_count_z
      - .offset:         452
        .size:           2
        .value_kind:     hidden_group_size_x
      - .offset:         454
        .size:           2
        .value_kind:     hidden_group_size_y
      - .offset:         456
        .size:           2
        .value_kind:     hidden_group_size_z
      - .offset:         458
        .size:           2
        .value_kind:     hidden_remainder_x
      - .offset:         460
        .size:           2
        .value_kind:     hidden_remainder_y
      - .offset:         462
        .size:           2
        .value_kind:     hidden_remainder_z
      - .offset:         480
        .size:           8
        .value_kind:     hidden_global_offset_x
      - .offset:         488
        .size:           8
        .value_kind:     hidden_global_offset_y
      - .offset:         496
        .size:           8
        .value_kind:     hidden_global_offset_z
      - .offset:         504
        .size:           2
        .value_kind:     hidden_grid_dims
      - .offset:         560
        .size:           4
        .value_kind:     hidden_dynamic_lds_size
    .group_segment_fixed_size: 0
    .kernarg_segment_align: 8
    .kernarg_segment_size: 696
    .language:       OpenCL C
    .language_version:
      - 2
      - 0
    .max_flat_workgroup_size: 512
    .name:           _Z3fwd4Args
    .private_segment_fixed_size: 0
    .sgpr_count:     108
    .sgpr_spill_count: 400
    .symbol:         _Z3fwd4Args.kd
    .uniform_work_group_size: 1
    .uses_dynamic_stack: false
    .vgpr_count:     256
    .vgpr_spill_count: 0
    .wavefront_size: 64
